# v50: topk threshold via 32-step bitwise search (1 v_cmp per bit per half + scalar popcount/select) instead of 64-way counting
# speedup vs baseline: 1.1482x; 1.0037x over previous
; __device__ void topk_unit(const Params& p, unsigned char* smem, int unit) {
;     ...
;   for (int tk = 0; tk < 16; ++tk) {
;     const unsigned* row = S + tk * 260;
;     unsigned ka[2], kb[2], mxk[2];
; #pragma unroll
;     for (int hf = 0; hf < 2; ++hf) {
;       ka[hf] = row[hf * 128 + lane];
;       kb[hf] = row[hf * 128 + 64 + lane];
;       mxk[hf] = ka[hf] > kb[hf] ? ka[hf] : kb[hf];
;       Ms[hf * 96 + lane] = mxk[hf];
;     }
;     int cnt[2][4];
; #pragma unroll
;     for (int hf = 0; hf < 2; ++hf)
; #pragma unroll
;       for (int e = 0; e < 4; ++e) cnt[hf][e] = 0;
; #pragma unroll
;     for (int j = 0; j < 16; ++j)
; #pragma unroll
;       for (int hf = 0; hf < 2; ++hf) {
;         u32x4 x = *(const u32x4*)(Ms + hf * 96 + j * 4);
; #pragma unroll
;         for (int e = 0; e < 4; ++e) cnt[hf][e] += (x[e] > mxk[hf]) ? 1 : 0;
;       }
;     bool ca_[2], cb_[2];
;     int pa[2], pb[2], ncand[2];
;     const unsigned long long lt = (1ull << lane) - 1ull;
; #pragma unroll
;     for (int hf = 0; hf < 2; ++hf) {
;       const int c_ = cnt[hf][0] + cnt[hf][1] + cnt[hf][2] + cnt[hf][3];
;       const unsigned long long bm = __ballot(c_ == 15);
;       const int srcT = __ffsll((long long)bm) - 1;
;       const unsigned T0 = (unsigned)__shfl((int)mxk[hf], srcT);
;       ca_[hf] = ka[hf] >= T0;
;       cb_[hf] = kb[hf] >= T0;
.Ltk2_loop:
	v_add_u32_e32 v8, s12, v103
	ds_read2st64_b32 v[2:3], v8 offset1:1
	ds_read2st64_b32 v[4:5], v8 offset0:2 offset1:3
	v_mov_b32_e32 v9, 0
	v_mov_b32_e32 v10, 0
	v_mov_b32_e32 v11, 0
	v_mov_b32_e32 v95, 0
	s_waitcnt lgkmcnt(0)
	v_max_u32_e32 v6, v2, v3
	v_max_u32_e32 v7, v4, v5
	ds_write_b32 v104, v6
	ds_write_b32 v104, v7 offset:384
	s_mov_b32 s84, 0
	s_mov_b32 s85, 0
	s_or_b32 s86, s84, 0x80000000
	s_or_b32 s87, s85, 0x80000000
	v_cmp_ge_u32_e64 s[68:69], v6, s86
	v_cmp_ge_u32_e64 s[70:71], v7, s87
	s_bcnt1_i32_b64 s72, s[68:69]
	s_bcnt1_i32_b64 s73, s[70:71]
	s_cmp_ge_u32 s72, 16
	s_cselect_b32 s84, s86, s84
	s_cmp_ge_u32 s73, 16
	s_cselect_b32 s85, s87, s85
	s_or_b32 s86, s84, 0x40000000
	s_or_b32 s87, s85, 0x40000000
	v_cmp_ge_u32_e64 s[68:69], v6, s86
	v_cmp_ge_u32_e64 s[70:71], v7, s87
	s_bcnt1_i32_b64 s72, s[68:69]
	s_bcnt1_i32_b64 s73, s[70:71]
	s_cmp_ge_u32 s72, 16
	s_cselect_b32 s84, s86, s84
	s_cmp_ge_u32 s73, 16
	s_cselect_b32 s85, s87, s85
	s_or_b32 s86, s84, 0x20000000
	s_or_b32 s87, s85, 0x20000000
	v_cmp_ge_u32_e64 s[68:69], v6, s86
	v_cmp_ge_u32_e64 s[70:71], v7, s87
	s_bcnt1_i32_b64 s72, s[68:69]
	s_bcnt1_i32_b64 s73, s[70:71]
	s_cmp_ge_u32 s72, 16
	s_cselect_b32 s84, s86, s84
	s_cmp_ge_u32 s73, 16
	s_cselect_b32 s85, s87, s85
	s_or_b32 s86, s84, 0x10000000
	s_or_b32 s87, s85, 0x10000000
	v_cmp_ge_u32_e64 s[68:69], v6, s86
	v_cmp_ge_u32_e64 s[70:71], v7, s87
	s_bcnt1_i32_b64 s72, s[68:69]
	s_bcnt1_i32_b64 s73, s[70:71]
	s_cmp_ge_u32 s72, 16
	s_cselect_b32 s84, s86, s84
	s_cmp_ge_u32 s73, 16
	s_cselect_b32 s85, s87, s85
	s_or_b32 s86, s84, 0x8000000
	s_or_b32 s87, s85, 0x8000000
	v_cmp_ge_u32_e64 s[68:69], v6, s86
	v_cmp_ge_u32_e64 s[70:71], v7, s87
	s_bcnt1_i32_b64 s72, s[68:69]
	s_bcnt1_i32_b64 s73, s[70:71]
	s_cmp_ge_u32 s72, 16
	s_cselect_b32 s84, s86, s84
	s_cmp_ge_u32 s73, 16
	s_cselect_b32 s85, s87, s85
	s_or_b32 s86, s84, 0x4000000
	s_or_b32 s87, s85, 0x4000000
	v_cmp_ge_u32_e64 s[68:69], v6, s86
	v_cmp_ge_u32_e64 s[70:71], v7, s87
	s_bcnt1_i32_b64 s72, s[68:69]
	s_bcnt1_i32_b64 s73, s[70:71]
	s_cmp_ge_u32 s72, 16
	s_cselect_b32 s84, s86, s84
	s_cmp_ge_u32 s73, 16
	s_cselect_b32 s85, s87, s85
	s_or_b32 s86, s84, 0x2000000
	s_or_b32 s87, s85, 0x2000000
	v_cmp_ge_u32_e64 s[68:69], v6, s86
	v_cmp_ge_u32_e64 s[70:71], v7, s87
	s_bcnt1_i32_b64 s72, s[68:69]
	s_bcnt1_i32_b64 s73, s[70:71]
	s_cmp_ge_u32 s72, 16
	s_cselect_b32 s84, s86, s84
	s_cmp_ge_u32 s73, 16
	s_cselect_b32 s85, s87, s85
	s_or_b32 s86, s84, 0x1000000
	s_or_b32 s87, s85, 0x1000000
	v_cmp_ge_u32_e64 s[68:69], v6, s86
	v_cmp_ge_u32_e64 s[70:71], v7, s87
	s_bcnt1_i32_b64 s72, s[68:69]
	s_bcnt1_i32_b64 s73, s[70:71]
	s_cmp_ge_u32 s72, 16
	s_cselect_b32 s84, s86, s84
	s_cmp_ge_u32 s73, 16
	s_cselect_b32 s85, s87, s85
	s_or_b32 s86, s84, 0x800000
	s_or_b32 s87, s85, 0x800000
	v_cmp_ge_u32_e64 s[68:69], v6, s86
	v_cmp_ge_u32_e64 s[70:71], v7, s87
	s_bcnt1_i32_b64 s72, s[68:69]
	s_bcnt1_i32_b64 s73, s[70:71]
	s_cmp_ge_u32 s72, 16
	s_cselect_b32 s84, s86, s84
	s_cmp_ge_u32 s73, 16
	s_cselect_b32 s85, s87, s85
	s_or_b32 s86, s84, 0x400000
	s_or_b32 s87, s85, 0x400000
	v_cmp_ge_u32_e64 s[68:69], v6, s86
	v_cmp_ge_u32_e64 s[70:71], v7, s87
	s_bcnt1_i32_b64 s72, s[68:69]
	s_bcnt1_i32_b64 s73, s[70:71]
	s_cmp_ge_u32 s72, 16
	s_cselect_b32 s84, s86, s84
	s_cmp_ge_u32 s73, 16
	s_cselect_b32 s85, s87, s85
	s_or_b32 s86, s84, 0x200000
	s_or_b32 s87, s85, 0x200000
	v_cmp_ge_u32_e64 s[68:69], v6, s86
	v_cmp_ge_u32_e64 s[70:71], v7, s87
	s_bcnt1_i32_b64 s72, s[68:69]
	s_bcnt1_i32_b64 s73, s[70:71]
	s_cmp_ge_u32 s72, 16
	s_cselect_b32 s84, s86, s84
	s_cmp_ge_u32 s73, 16
	s_cselect_b32 s85, s87, s85
	s_or_b32 s86, s84, 0x100000
	s_or_b32 s87, s85, 0x100000
	v_cmp_ge_u32_e64 s[68:69], v6, s86
	v_cmp_ge_u32_e64 s[70:71], v7, s87
	s_bcnt1_i32_b64 s72, s[68:69]
	s_bcnt1_i32_b64 s73, s[70:71]
	s_cmp_ge_u32 s72, 16
	s_cselect_b32 s84, s86, s84
	s_cmp_ge_u32 s73, 16
	s_cselect_b32 s85, s87, s85
	s_or_b32 s86, s84, 0x80000
	s_or_b32 s87, s85, 0x80000
	v_cmp_ge_u32_e64 s[68:69], v6, s86
	v_cmp_ge_u32_e64 s[70:71], v7, s87
	s_bcnt1_i32_b64 s72, s[68:69]
	s_bcnt1_i32_b64 s73, s[70:71]
	s_cmp_ge_u32 s72, 16
	s_cselect_b32 s84, s86, s84
	s_cmp_ge_u32 s73, 16
	s_cselect_b32 s85, s87, s85
	s_or_b32 s86, s84, 0x40000
	s_or_b32 s87, s85, 0x40000
	v_cmp_ge_u32_e64 s[68:69], v6, s86
	v_cmp_ge_u32_e64 s[70:71], v7, s87
	s_bcnt1_i32_b64 s72, s[68:69]
	s_bcnt1_i32_b64 s73, s[70:71]
	s_cmp_ge_u32 s72, 16
	s_cselect_b32 s84, s86, s84
	s_cmp_ge_u32 s73, 16
	s_cselect_b32 s85, s87, s85
	s_or_b32 s86, s84, 0x20000
	s_or_b32 s87, s85, 0x20000
	v_cmp_ge_u32_e64 s[68:69], v6, s86
	v_cmp_ge_u32_e64 s[70:71], v7, s87
	s_bcnt1_i32_b64 s72, s[68:69]
	s_bcnt1_i32_b64 s73, s[70:71]
	s_cmp_ge_u32 s72, 16
	s_cselect_b32 s84, s86, s84
	s_cmp_ge_u32 s73, 16
	s_cselect_b32 s85, s87, s85
	s_or_b32 s86, s84, 0x10000
	s_or_b32 s87, s85, 0x10000
	v_cmp_ge_u32_e64 s[68:69], v6, s86
	v_cmp_ge_u32_e64 s[70:71], v7, s87
	s_bcnt1_i32_b64 s72, s[68:69]
	s_bcnt1_i32_b64 s73, s[70:71]
	s_cmp_ge_u32 s72, 16
	s_cselect_b32 s84, s86, s84
	s_cmp_ge_u32 s73, 16
	s_cselect_b32 s85, s87, s85
	s_or_b32 s86, s84, 0x8000
	s_or_b32 s87, s85, 0x8000
	v_cmp_ge_u32_e64 s[68:69], v6, s86
	v_cmp_ge_u32_e64 s[70:71], v7, s87
	s_bcnt1_i32_b64 s72, s[68:69]
	s_bcnt1_i32_b64 s73, s[70:71]
	s_cmp_ge_u32 s72, 16
	s_cselect_b32 s84, s86, s84
	s_cmp_ge_u32 s73, 16
	s_cselect_b32 s85, s87, s85
	s_or_b32 s86, s84, 0x4000
	s_or_b32 s87, s85, 0x4000
	v_cmp_ge_u32_e64 s[68:69], v6, s86
	v_cmp_ge_u32_e64 s[70:71], v7, s87
	s_bcnt1_i32_b64 s72, s[68:69]
	s_bcnt1_i32_b64 s73, s[70:71]
	s_cmp_ge_u32 s72, 16
	s_cselect_b32 s84, s86, s84
; __device__ void topk_unit(const Params& p, unsigned char* smem, int unit) {
;     ...
;     bool ca_[2], cb_[2];
;     int pa[2], pb[2], ncand[2];
;     const unsigned long long lt = (1ull << lane) - 1ull;
; #pragma unroll
;     for (int hf = 0; hf < 2; ++hf) {
;       const int c_ = cnt[hf][0] + cnt[hf][1] + cnt[hf][2] + cnt[hf][3];
;       const unsigned long long bm = __ballot(c_ == 15);
;       const int srcT = __ffsll((long long)bm) - 1;
;       const unsigned T0 = (unsigned)__shfl((int)mxk[hf], srcT);
;       ca_[hf] = ka[hf] >= T0;
;       cb_[hf] = kb[hf] >= T0;
;       const unsigned long long ba = __ballot(ca_[hf]), bb = __ballot(cb_[hf]);
;       const int na = __popcll(ba);
;       pa[hf] = __popcll(ba & lt);
;       pb[hf] = na + __popcll(bb & lt);
;       ncand[hf] = na + __popcll(bb);
;     }
; #pragma unroll
;     for (int hf = 0; hf < 2; ++hf) {
;       unsigned* Cs = Ms + hf * 96 + 64;
;       if (lane < 32) Cs[lane] = 0u;
;       if (ca_[hf]) Cs[pa[hf]] = ka[hf];
;       if (cb_[hf]) Cs[pb[hf]] = kb[hf];
;     }
;     unsigned my[2];
;     int rk2[2][4];
; #pragma unroll
;     for (int hf = 0; hf < 2; ++hf) {
;       my[hf] = Ms[hf * 96 + 64 + (lane & 31)];
; #pragma unroll
;       for (int e = 0; e < 4; ++e) rk2[hf][e] = 0;
;     }
; #pragma unroll
;     for (int j = 0; j < 8; ++j)
; #pragma unroll
;       for (int hf = 0; hf < 2; ++hf) {
;         u32x4 x = *(const u32x4*)(Ms + hf * 96 + 64 + j * 4);
; #pragma unroll
;         for (int e = 0; e < 4; ++e) rk2[hf][e] += (x[e] > my[hf]) ? 1 : 0;
;       }
	s_cmp_ge_u32 s73, 16
	s_cselect_b32 s85, s87, s85
	s_or_b32 s86, s84, 0x2000
	s_or_b32 s87, s85, 0x2000
	v_cmp_ge_u32_e64 s[68:69], v6, s86
	v_cmp_ge_u32_e64 s[70:71], v7, s87
	s_bcnt1_i32_b64 s72, s[68:69]
	s_bcnt1_i32_b64 s73, s[70:71]
	s_cmp_ge_u32 s72, 16
	s_cselect_b32 s84, s86, s84
	s_cmp_ge_u32 s73, 16
	s_cselect_b32 s85, s87, s85
	s_or_b32 s86, s84, 0x1000
	s_or_b32 s87, s85, 0x1000
	v_cmp_ge_u32_e64 s[68:69], v6, s86
	v_cmp_ge_u32_e64 s[70:71], v7, s87
	s_bcnt1_i32_b64 s72, s[68:69]
	s_bcnt1_i32_b64 s73, s[70:71]
	s_cmp_ge_u32 s72, 16
	s_cselect_b32 s84, s86, s84
	s_cmp_ge_u32 s73, 16
	s_cselect_b32 s85, s87, s85
	s_or_b32 s86, s84, 0x800
	s_or_b32 s87, s85, 0x800
	v_cmp_ge_u32_e64 s[68:69], v6, s86
	v_cmp_ge_u32_e64 s[70:71], v7, s87
	s_bcnt1_i32_b64 s72, s[68:69]
	s_bcnt1_i32_b64 s73, s[70:71]
	s_cmp_ge_u32 s72, 16
	s_cselect_b32 s84, s86, s84
	s_cmp_ge_u32 s73, 16
	s_cselect_b32 s85, s87, s85
	s_or_b32 s86, s84, 0x400
	s_or_b32 s87, s85, 0x400
	v_cmp_ge_u32_e64 s[68:69], v6, s86
	v_cmp_ge_u32_e64 s[70:71], v7, s87
	s_bcnt1_i32_b64 s72, s[68:69]
	s_bcnt1_i32_b64 s73, s[70:71]
	s_cmp_ge_u32 s72, 16
	s_cselect_b32 s84, s86, s84
	s_cmp_ge_u32 s73, 16
	s_cselect_b32 s85, s87, s85
	s_or_b32 s86, s84, 0x200
	s_or_b32 s87, s85, 0x200
	v_cmp_ge_u32_e64 s[68:69], v6, s86
	v_cmp_ge_u32_e64 s[70:71], v7, s87
	s_bcnt1_i32_b64 s72, s[68:69]
	s_bcnt1_i32_b64 s73, s[70:71]
	s_cmp_ge_u32 s72, 16
	s_cselect_b32 s84, s86, s84
	s_cmp_ge_u32 s73, 16
	s_cselect_b32 s85, s87, s85
	s_or_b32 s86, s84, 0x100
	s_or_b32 s87, s85, 0x100
	v_cmp_ge_u32_e64 s[68:69], v6, s86
	v_cmp_ge_u32_e64 s[70:71], v7, s87
	s_bcnt1_i32_b64 s72, s[68:69]
	s_bcnt1_i32_b64 s73, s[70:71]
	s_cmp_ge_u32 s72, 16
	s_cselect_b32 s84, s86, s84
	s_cmp_ge_u32 s73, 16
	s_cselect_b32 s85, s87, s85
	s_or_b32 s86, s84, 0x80
	s_or_b32 s87, s85, 0x80
	v_cmp_ge_u32_e64 s[68:69], v6, s86
	v_cmp_ge_u32_e64 s[70:71], v7, s87
	s_bcnt1_i32_b64 s72, s[68:69]
	s_bcnt1_i32_b64 s73, s[70:71]
	s_cmp_ge_u32 s72, 16
	s_cselect_b32 s84, s86, s84
	s_cmp_ge_u32 s73, 16
	s_cselect_b32 s85, s87, s85
	s_or_b32 s86, s84, 64
	s_or_b32 s87, s85, 64
	v_cmp_ge_u32_e64 s[68:69], v6, s86
	v_cmp_ge_u32_e64 s[70:71], v7, s87
	s_bcnt1_i32_b64 s72, s[68:69]
	s_bcnt1_i32_b64 s73, s[70:71]
	s_cmp_ge_u32 s72, 16
	s_cselect_b32 s84, s86, s84
	s_cmp_ge_u32 s73, 16
	s_cselect_b32 s85, s87, s85
	s_or_b32 s86, s84, 32
	s_or_b32 s87, s85, 32
	v_cmp_ge_u32_e64 s[68:69], v6, s86
	v_cmp_ge_u32_e64 s[70:71], v7, s87
	s_bcnt1_i32_b64 s72, s[68:69]
	s_bcnt1_i32_b64 s73, s[70:71]
	s_cmp_ge_u32 s72, 16
	s_cselect_b32 s84, s86, s84
	s_cmp_ge_u32 s73, 16
	s_cselect_b32 s85, s87, s85
	s_or_b32 s86, s84, 16
	s_or_b32 s87, s85, 16
	v_cmp_ge_u32_e64 s[68:69], v6, s86
	v_cmp_ge_u32_e64 s[70:71], v7, s87
	s_bcnt1_i32_b64 s72, s[68:69]
	s_bcnt1_i32_b64 s73, s[70:71]
	s_cmp_ge_u32 s72, 16
	s_cselect_b32 s84, s86, s84
	s_cmp_ge_u32 s73, 16
	s_cselect_b32 s85, s87, s85
	s_or_b32 s86, s84, 8
	s_or_b32 s87, s85, 8
	v_cmp_ge_u32_e64 s[68:69], v6, s86
	v_cmp_ge_u32_e64 s[70:71], v7, s87
	s_bcnt1_i32_b64 s72, s[68:69]
	s_bcnt1_i32_b64 s73, s[70:71]
	s_cmp_ge_u32 s72, 16
	s_cselect_b32 s84, s86, s84
	s_cmp_ge_u32 s73, 16
	s_cselect_b32 s85, s87, s85
	s_or_b32 s86, s84, 4
	s_or_b32 s87, s85, 4
	v_cmp_ge_u32_e64 s[68:69], v6, s86
	v_cmp_ge_u32_e64 s[70:71], v7, s87
	s_bcnt1_i32_b64 s72, s[68:69]
	s_bcnt1_i32_b64 s73, s[70:71]
	s_cmp_ge_u32 s72, 16
	s_cselect_b32 s84, s86, s84
	s_cmp_ge_u32 s73, 16
	s_cselect_b32 s85, s87, s85
	s_or_b32 s86, s84, 2
	s_or_b32 s87, s85, 2
	v_cmp_ge_u32_e64 s[68:69], v6, s86
	v_cmp_ge_u32_e64 s[70:71], v7, s87
	s_bcnt1_i32_b64 s72, s[68:69]
	s_bcnt1_i32_b64 s73, s[70:71]
	s_cmp_ge_u32 s72, 16
	s_cselect_b32 s84, s86, s84
	s_cmp_ge_u32 s73, 16
	s_cselect_b32 s85, s87, s85
	s_or_b32 s86, s84, 1
	s_or_b32 s87, s85, 1
	v_cmp_ge_u32_e64 s[68:69], v6, s86
	v_cmp_ge_u32_e64 s[70:71], v7, s87
	s_bcnt1_i32_b64 s72, s[68:69]
	s_bcnt1_i32_b64 s73, s[70:71]
	s_cmp_ge_u32 s72, 16
	s_cselect_b32 s84, s86, s84
	s_cmp_ge_u32 s73, 16
	s_cselect_b32 s85, s87, s85
	s_nop 1
	v_cmp_ge_u32_e64 s[86:87], v2, s84
	v_cmp_ge_u32_e64 s[88:89], v3, s84
	v_cmp_ge_u32_e64 s[68:69], v4, s85
	v_cmp_ge_u32_e64 s[70:71], v5, s85
	s_nop 1
	s_bcnt1_i32_b64 s72, s[86:87]
	s_bcnt1_i32_b64 s73, s[68:69]
	v_mbcnt_lo_u32_b32 v44, s86, 0
	v_mbcnt_lo_u32_b32 v45, s88, 0
	v_mbcnt_lo_u32_b32 v46, s68, 0
	v_mbcnt_lo_u32_b32 v47, s70, 0
	v_mbcnt_hi_u32_b32 v44, s87, v44
	v_mbcnt_hi_u32_b32 v45, s89, v45
	v_mbcnt_hi_u32_b32 v46, s69, v46
	v_mbcnt_hi_u32_b32 v47, s71, v47
	v_add_u32_e32 v45, s72, v45
	v_add_u32_e32 v47, s73, v47
	v_lshl_add_u32 v44, v44, 2, v101
	v_lshl_add_u32 v45, v45, 2, v101
	v_lshl_add_u32 v46, v46, 2, v101
	v_lshl_add_u32 v47, v47, 2, v101
	s_mov_b64 exec, s[14:15]
	ds_write_b32 v105, v63 offset:256
	ds_write_b32 v105, v63 offset:640
	s_mov_b64 exec, s[86:87]
	ds_write_b32 v44, v2 offset:256
	s_mov_b64 exec, s[88:89]
	ds_write_b32 v45, v3 offset:256
	s_mov_b64 exec, s[68:69]
	ds_write_b32 v46, v4 offset:640
	s_mov_b64 exec, s[70:71]
	ds_write_b32 v47, v5 offset:640
	s_mov_b64 exec, s[46:47]
	ds_read_b32 v48, v89 offset:256
	ds_read_b128 v[12:15], v79 offset:256
	ds_read_b128 v[16:19], v79 offset:272
	ds_read_b128 v[20:23], v79 offset:288
	ds_read_b128 v[24:27], v79 offset:304
	ds_read_b128 v[28:31], v79 offset:320
	ds_read_b128 v[32:35], v79 offset:336
	ds_read_b128 v[36:39], v79 offset:352
	ds_read_b128 v[40:43], v79 offset:368
	v_mov_b32_e32 v49, 0
	v_mov_b32_e32 v50, 0
	s_waitcnt lgkmcnt(0)
; __device__ void topk_unit(const Params& p, unsigned char* smem, int unit) {
;     ...
; #pragma unroll
;     for (int j = 0; j < 8; ++j)
; #pragma unroll
;       for (int hf = 0; hf < 2; ++hf) {
;         u32x4 x = *(const u32x4*)(Ms + hf * 96 + 64 + j * 4);
; #pragma unroll
;         for (int e = 0; e < 4; ++e) rk2[hf][e] += (x[e] > my[hf]) ? 1 : 0;
;       }
; #pragma unroll
;     for (int hf = 0; hf < 2; ++hf) {
;       const int r_ = rk2[hf][0] + rk2[hf][1] + rk2[hf][2] + rk2[hf][3];
;       if (lane < ncand[hf] && r_ < 16) {
;         tops[hf * 16 + r_] = ord_dec(my[hf] & ~127u);
;         topi[hf * 16 + r_] = 127 - (int)(my[hf] & 127u);
;       }
;     }
;     float cs = 0.f;
;     unsigned ck = 0u;
;     if (lane < 50) {
;       cs = tops[ca] + tops[16 + cbb];
;       ck = (ord_key(cs) & ~255u) | (unsigned)(255 - (ca * 16 + cbb));
;     }
;     int rkA = 0, rkB = 0;
; #pragma unroll
;     for (int j = 0; j < 50; j += 2) {
;       const unsigned oj = (unsigned)__builtin_amdgcn_readlane((int)ck, j);
;       const unsigned oj2 = (unsigned)__builtin_amdgcn_readlane((int)ck, j + 1);
;       rkA += (oj > ck) ? 1 : 0;
;       rkB += (oj2 > ck) ? 1 : 0;
;     }
	v_cmp_gt_u32_e64 s[68:69], v12, v48
	v_cmp_gt_u32_e64 s[70:71], v13, v48
	v_cmp_gt_u32_e64 s[72:73], v14, v48
	v_cmp_gt_u32_e64 s[74:75], v15, v48
	v_addc_co_u32_e64 v49, s[76:77], 0, v49, s[68:69]
	v_addc_co_u32_e64 v50, s[76:77], 0, v50, s[70:71]
	v_addc_co_u32_e64 v49, s[76:77], 0, v49, s[72:73]
	v_addc_co_u32_e64 v50, s[76:77], 0, v50, s[74:75]
	v_cmp_gt_u32_e64 s[68:69], v16, v48
	v_cmp_gt_u32_e64 s[70:71], v17, v48
	v_cmp_gt_u32_e64 s[72:73], v18, v48
	v_cmp_gt_u32_e64 s[74:75], v19, v48
	v_addc_co_u32_e64 v49, s[76:77], 0, v49, s[68:69]
	v_addc_co_u32_e64 v50, s[76:77], 0, v50, s[70:71]
	v_addc_co_u32_e64 v49, s[76:77], 0, v49, s[72:73]
	v_addc_co_u32_e64 v50, s[76:77], 0, v50, s[74:75]
	v_cmp_gt_u32_e64 s[68:69], v20, v48
	v_cmp_gt_u32_e64 s[70:71], v21, v48
	v_cmp_gt_u32_e64 s[72:73], v22, v48
	v_cmp_gt_u32_e64 s[74:75], v23, v48
	v_addc_co_u32_e64 v49, s[76:77], 0, v49, s[68:69]
	v_addc_co_u32_e64 v50, s[76:77], 0, v50, s[70:71]
	v_addc_co_u32_e64 v49, s[76:77], 0, v49, s[72:73]
	v_addc_co_u32_e64 v50, s[76:77], 0, v50, s[74:75]
	v_cmp_gt_u32_e64 s[68:69], v24, v48
	v_cmp_gt_u32_e64 s[70:71], v25, v48
	v_cmp_gt_u32_e64 s[72:73], v26, v48
	v_cmp_gt_u32_e64 s[74:75], v27, v48
	v_addc_co_u32_e64 v49, s[76:77], 0, v49, s[68:69]
	v_addc_co_u32_e64 v50, s[76:77], 0, v50, s[70:71]
	v_addc_co_u32_e64 v49, s[76:77], 0, v49, s[72:73]
	v_addc_co_u32_e64 v50, s[76:77], 0, v50, s[74:75]
	v_cmp_gt_u32_e64 s[68:69], v28, v48
	v_cmp_gt_u32_e64 s[70:71], v29, v48
	v_cmp_gt_u32_e64 s[72:73], v30, v48
	v_cmp_gt_u32_e64 s[74:75], v31, v48
	v_addc_co_u32_e64 v49, s[76:77], 0, v49, s[68:69]
	v_addc_co_u32_e64 v50, s[76:77], 0, v50, s[70:71]
	v_addc_co_u32_e64 v49, s[76:77], 0, v49, s[72:73]
	v_addc_co_u32_e64 v50, s[76:77], 0, v50, s[74:75]
	v_cmp_gt_u32_e64 s[68:69], v32, v48
	v_cmp_gt_u32_e64 s[70:71], v33, v48
	v_cmp_gt_u32_e64 s[72:73], v34, v48
	v_cmp_gt_u32_e64 s[74:75], v35, v48
	v_addc_co_u32_e64 v49, s[76:77], 0, v49, s[68:69]
	v_addc_co_u32_e64 v50, s[76:77], 0, v50, s[70:71]
	v_addc_co_u32_e64 v49, s[76:77], 0, v49, s[72:73]
	v_addc_co_u32_e64 v50, s[76:77], 0, v50, s[74:75]
	v_cmp_gt_u32_e64 s[68:69], v36, v48
	v_cmp_gt_u32_e64 s[70:71], v37, v48
	v_cmp_gt_u32_e64 s[72:73], v38, v48
	v_cmp_gt_u32_e64 s[74:75], v39, v48
	v_addc_co_u32_e64 v49, s[76:77], 0, v49, s[68:69]
	v_addc_co_u32_e64 v50, s[76:77], 0, v50, s[70:71]
	v_addc_co_u32_e64 v49, s[76:77], 0, v49, s[72:73]
	v_addc_co_u32_e64 v50, s[76:77], 0, v50, s[74:75]
	v_cmp_gt_u32_e64 s[68:69], v40, v48
	v_cmp_gt_u32_e64 s[70:71], v41, v48
	v_cmp_gt_u32_e64 s[72:73], v42, v48
	v_cmp_gt_u32_e64 s[74:75], v43, v48
	v_addc_co_u32_e64 v49, s[76:77], 0, v49, s[68:69]
	v_addc_co_u32_e64 v50, s[76:77], 0, v50, s[70:71]
	v_addc_co_u32_e64 v49, s[76:77], 0, v49, s[72:73]
	v_addc_co_u32_e64 v50, s[76:77], 0, v50, s[74:75]
	v_add_u32_e32 v49, v49, v50
	v_and_b32_e32 v51, 0xffffff80, v48
	v_cmp_gt_u32_e64 s[74:75], 16, v49
	v_ashrrev_i32_e32 v52, 31, v51
	v_and_b32_e32 v53, 0x7f, v48
	v_not_b32_e32 v52, v52
	v_sub_u32_e32 v53, 0x7f, v53
	v_or_b32_e32 v52, 0x80000000, v52
	v_lshl_add_u32 v54, v49, 2, v94
	v_xor_b32_e32 v51, v51, v52
	s_mov_b64 exec, s[74:75]
	ds_write_b32 v54, v51
	ds_write_b32 v54, v53 offset:128
	s_mov_b64 exec, s[46:47]
	ds_read_b32 v121, v113
	ds_read_b32 v122, v112 offset:64
	ds_read2_b32 v[124:125], v99 offset1:16
	ds_read_b32 v126, v113 offset:128
	ds_read_b32 v127, v112 offset:192
	s_waitcnt lgkmcnt(3)
	v_add_f32_e32 v128, v121, v122
	v_mov_b32_e32 v130, 0
	v_ashrrev_i32_e32 v129, 31, v128
	v_mov_b32_e32 v131, 0
	v_or_b32_e32 v129, 0x80000000, v129
	v_xor_b32_e32 v129, v128, v129
	v_and_or_b32 v129, v129, s3, v92
	v_cndmask_b32_e64 v129, 0, v129, s[4:5]
	ds_write_b32 v104, v129
	ds_read_b128 v[12:15], v101
	ds_read_b128 v[16:19], v101 offset:16
	ds_read_b128 v[20:23], v101 offset:32
	ds_read_b128 v[24:27], v101 offset:48
	ds_read_b128 v[28:31], v101 offset:64
	ds_read_b128 v[32:35], v101 offset:80
	ds_read_b128 v[36:39], v101 offset:96
	ds_read_b128 v[40:43], v101 offset:112
	s_waitcnt lgkmcnt(4)
	v_cmp_gt_u32_e64 s[68:69], v12, v129
	v_cmp_gt_u32_e64 s[70:71], v13, v129
	v_cmp_gt_u32_e64 s[72:73], v14, v129
	v_cmp_gt_u32_e64 s[74:75], v15, v129
	v_addc_co_u32_e64 v130, s[76:77], 0, v130, s[68:69]
	v_addc_co_u32_e64 v131, s[76:77], 0, v131, s[70:71]
	v_addc_co_u32_e64 v130, s[76:77], 0, v130, s[72:73]
	v_addc_co_u32_e64 v131, s[76:77], 0, v131, s[74:75]
	v_cmp_gt_u32_e64 s[68:69], v16, v129
	v_cmp_gt_u32_e64 s[70:71], v17, v129
	v_cmp_gt_u32_e64 s[72:73], v18, v129
	v_cmp_gt_u32_e64 s[74:75], v19, v129
	v_addc_co_u32_e64 v130, s[76:77], 0, v130, s[68:69]
	v_addc_co_u32_e64 v131, s[76:77], 0, v131, s[70:71]
	v_addc_co_u32_e64 v130, s[76:77], 0, v130, s[72:73]
	v_addc_co_u32_e64 v131, s[76:77], 0, v131, s[74:75]
	v_cmp_gt_u32_e64 s[68:69], v20, v129
	v_cmp_gt_u32_e64 s[70:71], v21, v129
	v_cmp_gt_u32_e64 s[72:73], v22, v129
	v_cmp_gt_u32_e64 s[74:75], v23, v129
	v_addc_co_u32_e64 v130, s[76:77], 0, v130, s[68:69]
	v_addc_co_u32_e64 v131, s[76:77], 0, v131, s[70:71]
	v_addc_co_u32_e64 v130, s[76:77], 0, v130, s[72:73]
	v_addc_co_u32_e64 v131, s[76:77], 0, v131, s[74:75]
	v_cmp_gt_u32_e64 s[68:69], v24, v129
	v_cmp_gt_u32_e64 s[70:71], v25, v129
	v_cmp_gt_u32_e64 s[72:73], v26, v129
	v_cmp_gt_u32_e64 s[74:75], v27, v129
	v_addc_co_u32_e64 v130, s[76:77], 0, v130, s[68:69]
	v_addc_co_u32_e64 v131, s[76:77], 0, v131, s[70:71]
	v_addc_co_u32_e64 v130, s[76:77], 0, v130, s[72:73]
	v_addc_co_u32_e64 v131, s[76:77], 0, v131, s[74:75]
	ds_read_b128 v[12:15], v101 offset:128
	ds_read_b128 v[16:19], v101 offset:144
	ds_read_b128 v[20:23], v101 offset:160
	ds_read_b128 v[24:27], v101 offset:176
	ds_read_b128 v[148:151], v101 offset:192
	s_waitcnt lgkmcnt(5)
; __device__ void topk_unit(const Params& p, unsigned char* smem, int unit) {
;     ...
;     int rkA = 0, rkB = 0;
; #pragma unroll
;     for (int j = 0; j < 50; j += 2) {
;       const unsigned oj = (unsigned)__builtin_amdgcn_readlane((int)ck, j);
;       const unsigned oj2 = (unsigned)__builtin_amdgcn_readlane((int)ck, j + 1);
;       rkA += (oj > ck) ? 1 : 0;
;       rkB += (oj2 > ck) ? 1 : 0;
;     }
;     const int rk = rkA + rkB;
;     const float mx = tops[0] + tops[16];
;     const bool sel = (lane < 50) && (rk < 16);
;     const float ev = sel ? __expf(cs - mx) : 0.f;
;     const float sum = wave_sum(ev);
;     if (sel) {
;       const size_t o = (size_t)(tok0 + tk) * 128 + h * 16 + rk;
;       idxo[o] = topi[ca] * 128 + topi[16 + cbb];
;       go[o] = ev * __builtin_amdgcn_rcpf(sum);
;     }
;   }
	v_cmp_gt_u32_e64 s[68:69], v28, v129
	v_cmp_gt_u32_e64 s[70:71], v29, v129
	v_cmp_gt_u32_e64 s[72:73], v30, v129
	v_cmp_gt_u32_e64 s[74:75], v31, v129
	v_addc_co_u32_e64 v130, s[76:77], 0, v130, s[68:69]
	v_addc_co_u32_e64 v131, s[76:77], 0, v131, s[70:71]
	v_addc_co_u32_e64 v130, s[76:77], 0, v130, s[72:73]
	v_addc_co_u32_e64 v131, s[76:77], 0, v131, s[74:75]
	v_cmp_gt_u32_e64 s[68:69], v32, v129
	v_cmp_gt_u32_e64 s[70:71], v33, v129
	v_cmp_gt_u32_e64 s[72:73], v34, v129
	v_cmp_gt_u32_e64 s[74:75], v35, v129
	v_addc_co_u32_e64 v130, s[76:77], 0, v130, s[68:69]
	v_addc_co_u32_e64 v131, s[76:77], 0, v131, s[70:71]
	v_addc_co_u32_e64 v130, s[76:77], 0, v130, s[72:73]
	v_addc_co_u32_e64 v131, s[76:77], 0, v131, s[74:75]
	v_cmp_gt_u32_e64 s[68:69], v36, v129
	v_cmp_gt_u32_e64 s[70:71], v37, v129
	v_cmp_gt_u32_e64 s[72:73], v38, v129
	v_cmp_gt_u32_e64 s[74:75], v39, v129
	v_addc_co_u32_e64 v130, s[76:77], 0, v130, s[68:69]
	v_addc_co_u32_e64 v131, s[76:77], 0, v131, s[70:71]
	v_addc_co_u32_e64 v130, s[76:77], 0, v130, s[72:73]
	v_addc_co_u32_e64 v131, s[76:77], 0, v131, s[74:75]
	v_cmp_gt_u32_e64 s[68:69], v40, v129
	v_cmp_gt_u32_e64 s[70:71], v41, v129
	v_cmp_gt_u32_e64 s[72:73], v42, v129
	v_cmp_gt_u32_e64 s[74:75], v43, v129
	v_addc_co_u32_e64 v130, s[76:77], 0, v130, s[68:69]
	v_addc_co_u32_e64 v131, s[76:77], 0, v131, s[70:71]
	v_addc_co_u32_e64 v130, s[76:77], 0, v130, s[72:73]
	v_addc_co_u32_e64 v131, s[76:77], 0, v131, s[74:75]
	s_waitcnt lgkmcnt(0)
	v_cmp_gt_u32_e64 s[68:69], v12, v129
	v_cmp_gt_u32_e64 s[70:71], v13, v129
	v_cmp_gt_u32_e64 s[72:73], v14, v129
	v_cmp_gt_u32_e64 s[74:75], v15, v129
	v_addc_co_u32_e64 v130, s[76:77], 0, v130, s[68:69]
	v_addc_co_u32_e64 v131, s[76:77], 0, v131, s[70:71]
	v_addc_co_u32_e64 v130, s[76:77], 0, v130, s[72:73]
	v_addc_co_u32_e64 v131, s[76:77], 0, v131, s[74:75]
	v_cmp_gt_u32_e64 s[68:69], v16, v129
	v_cmp_gt_u32_e64 s[70:71], v17, v129
	v_cmp_gt_u32_e64 s[72:73], v18, v129
	v_cmp_gt_u32_e64 s[74:75], v19, v129
	v_addc_co_u32_e64 v130, s[76:77], 0, v130, s[68:69]
	v_addc_co_u32_e64 v131, s[76:77], 0, v131, s[70:71]
	v_addc_co_u32_e64 v130, s[76:77], 0, v130, s[72:73]
	v_addc_co_u32_e64 v131, s[76:77], 0, v131, s[74:75]
	v_cmp_gt_u32_e64 s[68:69], v20, v129
	v_cmp_gt_u32_e64 s[70:71], v21, v129
	v_cmp_gt_u32_e64 s[72:73], v22, v129
	v_cmp_gt_u32_e64 s[74:75], v23, v129
	v_addc_co_u32_e64 v130, s[76:77], 0, v130, s[68:69]
	v_addc_co_u32_e64 v131, s[76:77], 0, v131, s[70:71]
	v_addc_co_u32_e64 v130, s[76:77], 0, v130, s[72:73]
	v_addc_co_u32_e64 v131, s[76:77], 0, v131, s[74:75]
	v_cmp_gt_u32_e64 s[68:69], v24, v129
	v_cmp_gt_u32_e64 s[70:71], v25, v129
	v_cmp_gt_u32_e64 s[72:73], v26, v129
	v_cmp_gt_u32_e64 s[74:75], v27, v129
	v_addc_co_u32_e64 v130, s[76:77], 0, v130, s[68:69]
	v_addc_co_u32_e64 v131, s[76:77], 0, v131, s[70:71]
	v_addc_co_u32_e64 v130, s[76:77], 0, v130, s[72:73]
	v_addc_co_u32_e64 v131, s[76:77], 0, v131, s[74:75]
	v_cmp_gt_u32_e64 s[68:69], v148, v129
	v_cmp_gt_u32_e64 s[70:71], v149, v129
	v_cmp_gt_u32_e64 s[72:73], v150, v129
	v_cmp_gt_u32_e64 s[74:75], v151, v129
	v_addc_co_u32_e64 v130, s[76:77], 0, v130, s[68:69]
	v_addc_co_u32_e64 v131, s[76:77], 0, v131, s[70:71]
	v_addc_co_u32_e64 v130, s[76:77], 0, v130, s[72:73]
	v_addc_co_u32_e64 v131, s[76:77], 0, v131, s[74:75]
	v_add_u32_e32 v130, v130, v131
	v_mov_b32_e32 v131, 0
	v_cmp_gt_u32_e64 s[78:79], 16, v130
	v_add_f32_e32 v132, v124, v125
	v_sub_f32_e32 v132, v128, v132
	s_and_b64 s[78:79], s[78:79], s[4:5]
	v_mul_f32_e32 v132, 0x3fb8aa3b, v132
	v_exp_f32_e32 v132, v132
	v_lshl_add_u32 v136, v126, 7, v127
	v_lshl_add_u64 v[140:141], v[90:91], 0, v[130:131]
	v_cndmask_b32_e64 v132, 0, v132, s[78:79]
	v_lshlrev_b64 v[140:141], 2, v[140:141]
	s_nop 0
	v_add_f32_dpp v133, v132, v132 quad_perm:[1,0,3,2] row_mask:0xf bank_mask:0xf
	v_lshl_add_u64 v[142:143], s[38:39], 0, v[140:141]
	v_lshl_add_u64 v[144:145], s[40:41], 0, v[140:141]
	v_add_f32_dpp v133, v133, v133 quad_perm:[2,3,0,1] row_mask:0xf bank_mask:0xf
	s_nop 1
	v_add_f32_dpp v133, v133, v133 row_half_mirror row_mask:0xf bank_mask:0xf
	s_nop 1
	v_add_f32_dpp v133, v133, v133 row_mirror row_mask:0xf bank_mask:0xf
	s_nop 1
	v_readlane_b32 s80, v133, 0
	v_readlane_b32 s81, v133, 16
	v_readlane_b32 s82, v133, 32
	v_readlane_b32 s83, v133, 48
	v_mov_b32_e32 v134, s80
	s_nop 0
	v_add_f32_e32 v134, s81, v134
	v_add_f32_e32 v134, s82, v134
	v_add_f32_e32 v134, s83, v134
	v_rcp_f32_e32 v134, v134
	s_nop 0
	v_mul_f32_e32 v135, v132, v134
	s_mov_b64 exec, s[78:79]
	global_store_dword v[142:143], v136, off
	global_store_dword v[144:145], v135, off
	s_mov_b64 exec, s[46:47]
	s_addk_i32 s12, 0x410
	v_lshl_add_u64 v[90:91], v[90:91], 0, s[44:45]
	s_cmpk_lg_i32 s12, 0x4100
	s_cbranch_scc1 .Ltk2_loop
